# grid barrier: non-leader workgroups poll the top-level generation word directly (per-XCD generation bump removed)
# baseline (speedup 1.0000x reference)
.LBB0_91:
	s_lshl_b32 s2, s96, 8
	s_add_u32 s2, s28, s2
	s_addc_u32 s3, s29, 0
	v_mov_b32_e32 v1, 0x1000
	v_mov_b32_e32 v3, 1
	global_atomic_add v3, v1, v3, s[2:3] offset:1024 sc0
	v_cvt_f32_u32_e32 v1, v2
	v_sub_u32_e32 v4, 0, v2
	v_rcp_iflag_f32_e32 v1, v1
	s_nop 0
	v_mul_f32_e32 v1, 0x4f7ffffe, v1
	v_cvt_u32_f32_e32 v1, v1
	v_mul_lo_u32 v4, v4, v1
	v_mul_hi_u32 v4, v1, v4
	v_add_u32_e32 v1, v1, v4
	s_waitcnt vmcnt(0)
	v_mul_hi_u32 v1, v3, v1
	v_mul_lo_u32 v4, v1, v2
	v_sub_u32_e32 v4, v3, v4
	v_add_u32_e32 v5, 1, v1
	v_cmp_ge_u32_e32 vcc, v4, v2
	v_add_u32_e32 v3, 1, v3
	s_nop 0
	v_cndmask_b32_e32 v1, v1, v5, vcc
	v_sub_u32_e32 v5, v4, v2
	v_cndmask_b32_e32 v4, v4, v5, vcc
	v_add_u32_e32 v5, 1, v1
	v_cmp_ge_u32_e32 vcc, v4, v2
	s_nop 1
	v_cndmask_b32_e32 v1, v1, v5, vcc
	v_mul_lo_u32 v4, v2, v1
	v_add_u32_e32 v2, v4, v2
	v_cmp_ne_u32_e32 vcc, v3, v2
	s_and_saveexec_b64 s[4:5], vcc
	s_xor_b64 s[4:5], exec, s[4:5]
	s_cbranch_execz .LBB0_105
	s_waitcnt lgkmcnt(0)
	v_mov_b32_e32 v0, 0x3500
	global_load_dword v0, v0, s[28:29] sc1
	s_add_u32 s8, s28, 0x3500
	s_addc_u32 s9, s29, 0
	s_waitcnt vmcnt(0)
	v_cmp_eq_u32_e32 vcc, v0, v1
	s_and_saveexec_b64 s[6:7], vcc
	s_cbranch_execz .LBB0_104
	s_mov_b32 s11, 1
	s_mov_b64 s[12:13], 0
	v_mov_b32_e32 v0, 0
	s_branch .LBB0_95

.LBB0_122:
	s_or_b64 exec, exec, s[4:5]
	v_mov_b32_e32 v0, 0x2000
	v_mov_b32_e32 v1, 1
	s_waitcnt vmcnt(0)
	buffer_inv sc1
	s_waitcnt vmcnt(0)

.LBB0_1648:
	s_lshl_b32 s2, s96, 8
	s_add_u32 s2, s28, s2
	s_addc_u32 s3, s29, 0
	v_mov_b32_e32 v1, 0x1000
	v_mov_b32_e32 v3, 1
	global_atomic_add v3, v1, v3, s[2:3] offset:1024 sc0
	v_cvt_f32_u32_e32 v1, v2
	v_sub_u32_e32 v4, 0, v2
	v_rcp_iflag_f32_e32 v1, v1
	s_nop 0
	v_mul_f32_e32 v1, 0x4f7ffffe, v1
	v_cvt_u32_f32_e32 v1, v1
	v_mul_lo_u32 v4, v4, v1
	v_mul_hi_u32 v4, v1, v4
	v_add_u32_e32 v1, v1, v4
	s_waitcnt vmcnt(0)
	v_mul_hi_u32 v1, v3, v1
	v_mul_lo_u32 v4, v1, v2
	v_sub_u32_e32 v4, v3, v4
	v_add_u32_e32 v5, 1, v1
	v_cmp_ge_u32_e32 vcc, v4, v2
	v_add_u32_e32 v3, 1, v3
	s_nop 0
	v_cndmask_b32_e32 v1, v1, v5, vcc
	v_sub_u32_e32 v5, v4, v2
	v_cndmask_b32_e32 v4, v4, v5, vcc
	v_add_u32_e32 v5, 1, v1
	v_cmp_ge_u32_e32 vcc, v4, v2
	s_nop 1
	v_cndmask_b32_e32 v1, v1, v5, vcc
	v_mul_lo_u32 v4, v2, v1
	v_add_u32_e32 v2, v4, v2
	v_cmp_ne_u32_e32 vcc, v3, v2
	s_and_saveexec_b64 s[4:5], vcc
	s_xor_b64 s[4:5], exec, s[4:5]
	s_cbranch_execz .LBB0_1662
	s_waitcnt lgkmcnt(0)
	v_mov_b32_e32 v0, 0x3500
	global_load_dword v0, v0, s[28:29] sc1
	s_add_u32 s8, s28, 0x3500
	s_addc_u32 s9, s29, 0
	s_waitcnt vmcnt(0)
	v_cmp_eq_u32_e32 vcc, v0, v1
	s_and_saveexec_b64 s[6:7], vcc
	s_cbranch_execz .LBB0_1661
	s_mov_b32 s20, 1
	s_mov_b64 s[10:11], 0
	v_mov_b32_e32 v0, 0
	s_branch .LBB0_1652
